# latent attention: the 32 softmax row-sum adds moved from the serial tail before the tile barrier to under the last PV and QK MFMAs (same add order)
# speedup vs baseline: 1.0048x; 1.0048x over previous
.LBB0_210:
	s_add_i32 s71, s64, 0x4000
	s_and_b32 s9, s71, 0x4000
	v_add_u32_e32 v179, s9, v177
	v_add_u32_e32 v197, v179, v176
	v_add_u32_e32 v202, v179, v175
	v_add_u32_e32 v203, v179, v173
	v_add_u32_e32 v204, v179, v171
	ds_read_b128 v[214:217], v197 offset:4096
	ds_read_b128 v[218:221], v202 offset:4096
	ds_read_b128 v[246:249], v203 offset:4096
	ds_read_b128 v[236:239], v204 offset:4096
	v_add_u32_e32 v205, s9, v174
	v_add_u32_e32 v206, v205, v176
	ds_read_b128 v[198:201], v206 offset:32768
	v_add_u32_e32 v207, v205, v175
	v_add_u32_e32 v208, v205, v173
	v_add_u32_e32 v205, v205, v171
	v_exp_f32_e32 v179, v80
	v_exp_f32_e32 v180, v81
	v_exp_f32_e32 v181, v82
	v_exp_f32_e32 v182, v83
	v_exp_f32_e32 v183, v84
	v_exp_f32_e32 v184, v85
	v_exp_f32_e32 v185, v86
	v_exp_f32_e32 v186, v87
	v_exp_f32_e32 v187, v88
	v_exp_f32_e32 v188, v89
	v_exp_f32_e32 v189, v90
	v_exp_f32_e32 v190, v91
	v_exp_f32_e32 v191, v92
	v_exp_f32_e32 v194, v93
	v_exp_f32_e32 v195, v94
	v_exp_f32_e32 v196, v95
	s_and_b32 s9, s64, 0x4000
	s_add_i32 s46, s9, 0
	v_add_u32_e32 v213, s46, v165
	s_andn2_b64 vcc, exec, s[0:1]
	s_waitcnt lgkmcnt(4)
	v_mfma_f32_32x32x16_bf16 v[80:95], v[214:217], v[112:115], v[64:79]
	ds_read_b128 v[214:217], v206 offset:36864
	v_exp_f32_e32 v209, v108
	s_waitcnt lgkmcnt(4)
	v_mfma_f32_32x32x16_bf16 v[80:95], v[218:221], v[116:119], v[80:95]
	ds_read_b128 v[218:221], v206 offset:40960
	v_exp_f32_e32 v210, v109
	s_waitcnt lgkmcnt(4)
	v_mfma_f32_32x32x16_bf16 v[80:95], v[246:249], v[120:123], v[80:95]
	ds_read_b128 v[246:249], v206 offset:45056
	v_exp_f32_e32 v206, v105
	s_waitcnt lgkmcnt(4)
	v_mfma_f32_32x32x16_bf16 v[80:95], v[236:239], v[124:127], v[80:95]
	ds_read_b128 v[236:239], v207 offset:32768
	v_exp_f32_e32 v211, v110
	s_waitcnt lgkmcnt(4)
	v_mfma_f32_32x32x16_bf16 v[48:63], v[198:201], v[148:151], v[48:63]
	ds_read_b128 v[198:201], v207 offset:36864
	v_exp_f32_e32 v212, v111
	s_waitcnt lgkmcnt(4)
	v_mfma_f32_32x32x16_bf16 v[32:47], v[214:217], v[148:151], v[32:47]
	ds_read_b128 v[214:217], v207 offset:40960
	s_waitcnt lgkmcnt(4)
	v_mfma_f32_32x32x16_bf16 v[16:31], v[218:221], v[148:151], v[16:31]
	ds_read_b128 v[218:221], v207 offset:45056
	v_exp_f32_e32 v207, v106
	s_waitcnt lgkmcnt(4)
	v_mfma_f32_32x32x16_bf16 v[0:15], v[246:249], v[148:151], v[0:15]
	ds_read_b128 v[246:249], v208 offset:32768
	s_waitcnt lgkmcnt(4)
	v_mfma_f32_32x32x16_bf16 v[48:63], v[236:239], v[144:147], v[48:63]
	ds_read_b128 v[236:239], v208 offset:36864
	s_waitcnt lgkmcnt(4)
	v_mfma_f32_32x32x16_bf16 v[32:47], v[198:201], v[144:147], v[32:47]
	ds_read_b128 v[198:201], v208 offset:40960
	s_waitcnt lgkmcnt(4)
	v_mfma_f32_32x32x16_bf16 v[16:31], v[214:217], v[144:147], v[16:31]
	ds_read_b128 v[214:217], v208 offset:45056
	v_exp_f32_e32 v208, v107
	s_waitcnt lgkmcnt(4)
	v_mfma_f32_32x32x16_bf16 v[0:15], v[218:221], v[144:147], v[0:15]
	ds_read_b128 v[218:221], v205 offset:32768
	s_waitcnt lgkmcnt(4)
	v_mfma_f32_32x32x16_bf16 v[48:63], v[246:249], v[140:143], v[48:63]
	ds_read_b128 v[246:249], v205 offset:36864
	s_waitcnt lgkmcnt(4)
	v_mfma_f32_32x32x16_bf16 v[32:47], v[236:239], v[140:143], v[32:47]
	ds_read_b128 v[236:239], v205 offset:40960
	s_waitcnt lgkmcnt(4)
	v_mfma_f32_32x32x16_bf16 v[16:31], v[198:201], v[140:143], v[16:31]
	ds_read_b128 v[148:151], v205 offset:45056
	v_exp_f32_e32 v205, v104
	v_exp_f32_e32 v198, v97
	v_exp_f32_e32 v199, v98
	s_waitcnt lgkmcnt(4)
	v_mfma_f32_32x32x16_bf16 v[0:15], v[214:217], v[140:143], v[0:15]
	ds_read_b128 v[214:217], v197
	v_exp_f32_e32 v197, v96
	v_exp_f32_e32 v200, v99
	v_exp_f32_e32 v201, v100
	s_waitcnt lgkmcnt(4)
	v_mfma_f32_32x32x16_bf16 v[48:63], v[218:221], v[136:139], v[48:63]
	ds_read_b128 v[218:221], v202
	v_exp_f32_e32 v202, v101
	v_add_f32_e32 v222, v197, v179
	v_add_f32_e32 v223, 0, v222
	v_add_f32_e32 v222, v198, v180
	v_add_f32_e32 v223, v222, v223
	v_add_f32_e32 v222, v199, v181
	v_add_f32_e32 v223, v222, v223
	s_waitcnt lgkmcnt(4)
	v_mfma_f32_32x32x16_bf16 v[32:47], v[246:249], v[136:139], v[32:47]
	ds_read_b128 v[246:249], v203
	v_exp_f32_e32 v203, v102
	v_add_f32_e32 v222, v200, v182
	v_add_f32_e32 v223, v222, v223
	v_add_f32_e32 v222, v201, v183
	v_add_f32_e32 v223, v222, v223
	v_add_f32_e32 v222, v202, v184
	v_add_f32_e32 v223, v222, v223
	s_waitcnt lgkmcnt(4)
	v_mfma_f32_32x32x16_bf16 v[16:31], v[236:239], v[136:139], v[16:31]
	ds_read_b128 v[236:239], v204
	v_exp_f32_e32 v204, v103
	v_add_f32_e32 v222, v203, v185
	v_add_f32_e32 v223, v222, v223
	s_waitcnt lgkmcnt(4)
	v_mfma_f32_32x32x16_bf16 v[0:15], v[148:151], v[136:139], v[0:15]
	v_add_f32_e32 v222, v204, v186
	v_add_f32_e32 v223, v222, v223
	v_cvt_pk_bf16_f32 v148, v197, v198
	v_cvt_pk_bf16_f32 v149, v199, v200
	v_cvt_pk_bf16_f32 v150, v201, v202
	v_cvt_pk_bf16_f32 v151, v203, v204
	v_cvt_pk_bf16_f32 v140, v179, v180
	v_cvt_pk_bf16_f32 v141, v181, v182
	v_cvt_pk_bf16_f32 v142, v183, v184
	s_waitcnt lgkmcnt(3)
	v_mfma_f32_32x32x16_bf16 v[96:111], v[214:217], v[112:115], v[64:79]
	v_add_f32_e32 v222, v205, v187
	v_add_f32_e32 v223, v222, v223
	v_add_f32_e32 v222, v206, v188
	v_add_f32_e32 v223, v222, v223
	v_add_f32_e32 v222, v207, v189
	v_add_f32_e32 v223, v222, v223
	v_add_f32_e32 v222, v208, v190
	v_add_f32_e32 v223, v222, v223
	v_add_u32_e32 v214, v213, v172
	v_cvt_pk_bf16_f32 v143, v185, v186
	v_cvt_pk_bf16_f32 v144, v205, v206
	v_cvt_pk_bf16_f32 v145, v207, v208
	v_cvt_pk_bf16_f32 v146, v209, v210
	v_cvt_pk_bf16_f32 v147, v211, v212
	v_cvt_pk_bf16_f32 v136, v187, v188
	s_waitcnt lgkmcnt(2)
	v_mfma_f32_32x32x16_bf16 v[96:111], v[218:221], v[116:119], v[96:111]
	v_add_f32_e32 v222, v209, v191
	v_add_f32_e32 v223, v222, v223
	v_add_f32_e32 v222, v210, v194
	v_add_f32_e32 v223, v222, v223
	v_add_f32_e32 v222, v211, v195
	v_add_f32_e32 v223, v222, v223
	v_add_f32_e32 v222, v212, v196
	v_add_f32_e32 v223, v222, v223
	v_add_f32_e32 v168, v168, v223
	v_cvt_pk_bf16_f32 v137, v189, v190
	v_cvt_pk_bf16_f32 v138, v191, v194
	v_cvt_pk_bf16_f32 v139, v195, v196
	s_waitcnt vmcnt(1)
	ds_write_b64 v214, v[152:153] offset:32768
	v_add_u32_e32 v152, v213, v169
	s_waitcnt vmcnt(0)
	ds_write_b64 v214, v[156:157] offset:40960
	ds_write2st64_b64 v152, v[154:155], v[158:159] offset0:64 offset1:80
	s_waitcnt lgkmcnt(4)
	v_mfma_f32_32x32x16_bf16 v[96:111], v[246:249], v[120:123], v[96:111]
	s_waitcnt lgkmcnt(3)
	v_mfma_f32_32x32x16_bf16 v[96:111], v[236:239], v[124:127], v[96:111]
	s_cbranch_vccnz .LBB0_212
	v_add_u32_e32 v152, s46, v170
	ds_write_b128 v152, v[128:131]
	ds_write_b128 v152, v[132:135] offset:8192
.LBB0_212:
	s_add_i32 s41, s41, 1
	v_add_u32_e32 v178, 0x2000, v178
	s_cmp_eq_u32 s41, 36
	v_add_u32_e32 v167, 0x80, v167
	s_waitcnt lgkmcnt(0)
	s_barrier
	s_cbranch_scc1 .LBB0_214
	s_mov_b32 s64, s71
	s_branch .LBB0_208
